# nt loads also for w_mod rows, f32 input rows in normmod1, cache_kv rows and the FFN-up-tail transposes
# speedup vs baseline: 1.0265x; 1.0145x over previous
.LBB0_167:
	s_cmp_gt_i32 s0, -1
	s_mov_b64 s[12:13], -1
	s_cbranch_scc0 .LBB0_169
	s_and_b32 s12, s0, 0xffff
	s_mulk_i32 s12, 0x4ec5
	s_lshr_b32 s13, s12, 21
	s_lshr_b32 s12, s12, 14
	s_mulk_i32 s13, 0x68
	s_and_b32 s12, s12, 0xff80
	s_sub_i32 s13, s0, s13
	s_mul_i32 s14, s12, 0x6800
	s_add_u32 s14, s16, s14
	s_addc_u32 s15, s17, 0
	s_lshl_b32 s13, s13, 6
	s_and_b32 s13, s13, 0xffc0
	v_mov_b32_e32 v8, v1
	s_lshl_b32 s18, s13, 2
	s_add_u32 s14, s14, s18
	v_lshlrev_b32_e32 v10, 4, v8
	s_addc_u32 s15, s15, 0
	v_and_b32_e32 v162, 0xf0, v10
	v_ashrrev_i32_e32 v9, 4, v8
	v_lshl_add_u64 v[6:7], s[14:15], 0, v[162:163]
	s_movk_i32 s18, 0x6800
	v_mad_i64_i32 v[2:3], s[14:15], v9, s18, v[6:7]
	global_load_dwordx4 v[2:5], v[2:3], off nt
	s_movk_i32 s14, 0x104
	v_mul_lo_u32 v11, v9, s14
	v_add3_u32 v11, 0, v162, v11
	v_add_u32_e32 v12, 0x2080, v11
	v_and_b32_e32 v13, 0x70, v10
	s_lshl_b32 s48, s12, 1
	v_lshlrev_b32_e32 v162, 1, v13
	s_waitcnt vmcnt(0)
	ds_write2_b32 v11, v2, v3 offset1:1
	ds_write2_b32 v11, v4, v5 offset0:2 offset1:3
	v_add_u32_e32 v2, 32, v9
	v_mad_i64_i32 v[2:3], s[14:15], v2, s18, v[6:7]
	global_load_dwordx4 v[2:5], v[2:3], off nt
	s_waitcnt vmcnt(0)
	ds_write2_b32 v12, v2, v3 offset1:1
	v_add_u32_e32 v2, 0x2088, v11
	ds_write2_b32 v2, v4, v5 offset1:1
	v_add_u32_e32 v2, 64, v9
	v_mad_i64_i32 v[2:3], s[14:15], v2, s18, v[6:7]
	global_load_dwordx4 v[2:5], v[2:3], off nt
	v_add_u32_e32 v12, 0x4100, v11
	s_waitcnt vmcnt(0)
	ds_write2_b32 v12, v2, v3 offset1:1
	v_add_u32_e32 v2, 0x4108, v11
	ds_write2_b32 v2, v4, v5 offset1:1
	v_add_u32_e32 v2, 0x60, v9
	v_mad_i64_i32 v[2:3], s[14:15], v2, s18, v[6:7]
	global_load_dwordx4 v[2:5], v[2:3], off nt
	v_add_u32_e32 v6, 0x6180, v11
	v_ashrrev_i32_e32 v12, 3, v8
	s_waitcnt vmcnt(0)
	ds_write2_b32 v6, v2, v3 offset1:1
	v_add_u32_e32 v2, 0x6188, v11
	ds_write2_b32 v2, v4, v5 offset1:1
	v_mul_u32_u24_e32 v2, 0x41, v13
	v_lshlrev_b32_e32 v4, 2, v12
	v_lshlrev_b32_e32 v5, 2, v2
	v_add3_u32 v8, 0, v4, v5
	v_add3_u32 v10, 0, v5, v4
	s_waitcnt lgkmcnt(0)
	s_barrier
	ds_read2_b32 v[2:3], v8 offset1:130
	ds_read2_b32 v[4:5], v10 offset0:65 offset1:195
	v_add_u32_e32 v14, 0xc00, v10
	s_waitcnt lgkmcnt(0)
	v_cvt_pk_bf16_f32 v2, v2, v4
	v_add_u32_e32 v4, 0x800, v10
	ds_read2_b32 v[6:7], v4 offset0:8 offset1:73
	v_cvt_pk_bf16_f32 v3, v3, v5
	ds_read2_b32 v[4:5], v4 offset0:138 offset1:203
	s_waitcnt lgkmcnt(1)
	v_cvt_pk_bf16_f32 v6, v6, v7
	s_waitcnt lgkmcnt(0)
	v_cvt_pk_bf16_f32 v7, v4, v5
	v_add_u32_e32 v4, 0x400, v8
	v_add_u32_e32 v8, 0x400, v10
	ds_read2_b32 v[4:5], v4 offset0:4 offset1:134
	ds_read2_b32 v[8:9], v8 offset0:69 offset1:199
	ds_read2_b32 v[10:11], v14 offset0:12 offset1:77
	s_waitcnt lgkmcnt(1)
	v_cvt_pk_bf16_f32 v4, v4, v8
	s_waitcnt lgkmcnt(0)
	v_cvt_pk_bf16_f32 v8, v10, v11
	ds_read2_b32 v[10:11], v14 offset0:142 offset1:207
	v_cvt_pk_bf16_f32 v5, v5, v9
	s_waitcnt lgkmcnt(0)
	v_cvt_pk_bf16_f32 v9, v10, v11
	v_add_u32_e32 v10, s13, v12
	v_ashrrev_i32_e32 v11, 31, v10
	v_lshlrev_b64 v[10:11], 11, v[10:11]
	v_lshl_add_u64 v[10:11], s[44:45], 0, v[10:11]
	v_lshl_add_u64 v[10:11], v[10:11], 0, s[48:49]
	v_lshl_add_u64 v[10:11], v[10:11], 0, v[162:163]
	global_store_dwordx4 v[10:11], v[2:5], off
	global_store_dwordx4 v[10:11], v[6:9], off offset:16
	s_barrier
	s_mov_b64 s[12:13], 0

.LBB0_643:
	s_waitcnt vmcnt(22)
	v_add_u32_e32 v44, 0xfffff000, v34
	v_cmp_gt_i32_e64 s[40:41], s93, v34
	v_mov_b32_e32 v4, s55
	v_mov_b32_e32 v5, s53
	v_cndmask_b32_e64 v3, 0, v35, s[40:41]
	v_cndmask_b32_e64 v2, v44, v34, s[40:41]
	v_cndmask_b32_e64 v5, v4, v5, s[40:41]
	v_mov_b32_e32 v4, s54
	v_mov_b32_e32 v6, s52
	v_lshlrev_b64 v[2:3], 12, v[2:3]
	v_cndmask_b32_e64 v4, v4, v6, s[40:41]
	v_lshl_add_u64 v[2:3], v[4:5], 0, v[2:3]
	v_cndmask_b32_e64 v4, 0, v2, s[38:39]
	v_mov_b32_e32 v2, v1
	v_cndmask_b32_e64 v5, 0, v3, s[38:39]
	v_mov_b32_e32 v39, v163
	v_lshlrev_b32_e32 v3, 2, v2
	v_and_b32_e32 v3, 0xfc, v3
	v_lshlrev_b32_e32 v38, 2, v3
	v_cmp_ne_u64_e64 s[42:43], 0, v[4:5]
	v_lshl_add_u64 v[40:41], v[4:5], 0, v[38:39]
	s_and_saveexec_b64 s[8:9], s[42:43]
	s_xor_b64 s[8:9], exec, s[8:9]
	s_cbranch_execz .LBB0_645
	global_load_dwordx4 v[14:17], v[40:41], off nt

.LBB0_647:
	s_or_b64 exec, exec, s[8:9]
	s_and_saveexec_b64 s[8:9], s[42:43]
	s_xor_b64 s[8:9], exec, s[8:9]
	s_cbranch_execz .LBB0_649
	global_load_dwordx4 v[10:13], v[40:41], off offset:1024 nt
	s_andn2_saveexec_b64 s[8:9], s[8:9]
	s_cbranch_execz .LBB0_651
	s_branch .LBB0_650

.LBB0_651:
	s_or_b64 exec, exec, s[8:9]
	s_and_saveexec_b64 s[8:9], s[42:43]
	s_xor_b64 s[8:9], exec, s[8:9]
	s_cbranch_execz .LBB0_653
	global_load_dwordx4 v[6:9], v[40:41], off offset:2048 nt
	s_andn2_saveexec_b64 s[8:9], s[8:9]
	s_cbranch_execz .LBB0_655
	s_branch .LBB0_654

.LBB0_655:
	s_or_b64 exec, exec, s[8:9]
	s_and_saveexec_b64 s[8:9], s[42:43]
	s_xor_b64 s[8:9], exec, s[8:9]
	s_cbranch_execz .LBB0_657
	global_load_dwordx4 v[2:5], v[40:41], off offset:3072 nt
	s_andn2_saveexec_b64 s[8:9], s[8:9]
	s_cbranch_execz .LBB0_659
	s_branch .LBB0_658

.LBB0_659:
	s_or_b64 exec, exec, s[8:9]
	s_and_saveexec_b64 s[8:9], s[42:43]
	s_xor_b64 s[8:9], exec, s[8:9]
	s_cbranch_execz .LBB0_661
	v_add_co_u32_e32 v18, vcc, 0x1000, v40
	s_nop 1
	v_addc_co_u32_e32 v19, vcc, 0, v41, vcc
	global_load_dwordx4 v[30:33], v[18:19], off nt
	s_andn2_saveexec_b64 s[8:9], s[8:9]
	s_cbranch_execz .LBB0_663
	s_branch .LBB0_662

.LBB0_663:
	s_or_b64 exec, exec, s[8:9]
	s_and_saveexec_b64 s[8:9], s[42:43]
	s_xor_b64 s[8:9], exec, s[8:9]
	s_cbranch_execz .LBB0_665
	v_add_co_u32_e32 v18, vcc, 0x1000, v40
	s_nop 1
	v_addc_co_u32_e32 v19, vcc, 0, v41, vcc
	global_load_dwordx4 v[26:29], v[18:19], off offset:1024 nt
	s_andn2_saveexec_b64 s[8:9], s[8:9]
	s_cbranch_execz .LBB0_667
	s_branch .LBB0_666

.LBB0_667:
	s_or_b64 exec, exec, s[8:9]
	s_and_saveexec_b64 s[8:9], s[42:43]
	s_xor_b64 s[8:9], exec, s[8:9]
	s_cbranch_execz .LBB0_669
	v_add_co_u32_e32 v18, vcc, 0x1000, v40
	s_nop 1
	v_addc_co_u32_e32 v19, vcc, 0, v41, vcc
	global_load_dwordx4 v[22:25], v[18:19], off offset:2048 nt
	s_andn2_saveexec_b64 s[8:9], s[8:9]
	s_cbranch_execz .LBB0_671
	s_branch .LBB0_670

.LBB0_671:
	s_or_b64 exec, exec, s[8:9]
	s_and_saveexec_b64 s[8:9], s[42:43]
	s_xor_b64 s[8:9], exec, s[8:9]
	s_cbranch_execz .LBB0_673
	v_add_co_u32_e32 v18, vcc, 0x1000, v40
	s_nop 1
	v_addc_co_u32_e32 v19, vcc, 0, v41, vcc
	global_load_dwordx4 v[18:21], v[18:19], off offset:3072 nt
	s_andn2_saveexec_b64 s[8:9], s[8:9]
	s_cbranch_execz .LBB0_642
	s_branch .LBB0_674

.LBB0_704:
	s_waitcnt vmcnt(30)
	v_lshl_add_u64 v[16:17], v[8:9], 0, s[8:9]
	global_load_dwordx4 v[12:15], v[16:17], off nt
	s_waitcnt vmcnt(30)
	v_add_co_u32_e32 v18, vcc, 0x1000, v16
	s_movk_i32 s10, 0x3000
	s_nop 0
	v_addc_co_u32_e32 v19, vcc, 0, v17, vcc
	v_add_co_u32_e32 v16, vcc, s10, v16
	s_add_u32 s8, s8, 0x4000
	s_nop 0
	v_addc_co_u32_e32 v17, vcc, 0, v17, vcc
	s_addc_u32 s9, s9, 0
	s_cmp_eq_u32 s8, 0x10000
	s_waitcnt vmcnt(0)
	v_cvt_pk_bf16_f32 v12, v12, v13
	v_cvt_pk_bf16_f32 v13, v14, v15
	global_store_dwordx2 v[6:7], v[12:13], off offset:-4096
	global_load_dwordx4 v[12:15], v[18:19], off nt
	s_waitcnt vmcnt(0)
	v_cvt_pk_bf16_f32 v12, v12, v13
	v_cvt_pk_bf16_f32 v13, v14, v15
	global_store_dwordx2 v[6:7], v[12:13], off offset:-2048
	global_load_dwordx4 v[12:15], v[16:17], off offset:-4096 nt
	s_waitcnt vmcnt(0)
	v_cvt_pk_bf16_f32 v12, v12, v13
	v_cvt_pk_bf16_f32 v13, v14, v15
	global_store_dwordx2 v[6:7], v[12:13], off
	global_load_dwordx4 v[12:15], v[16:17], off nt
	s_waitcnt vmcnt(0)
	v_cvt_pk_bf16_f32 v12, v12, v13
	v_cvt_pk_bf16_f32 v13, v14, v15
	global_store_dwordx2 v[6:7], v[12:13], off offset:2048
	v_lshl_add_u64 v[6:7], v[6:7], 0, s[34:35]
	s_cbranch_scc0 .LBB0_704
	v_add_u32_e32 v6, v10, v11
	v_add3_u32 v6, v6, v3, 8
	v_ashrrev_i32_e32 v7, 31, v6
	v_lshlrev_b32_e32 v162, 1, v2
	v_lshlrev_b64 v[6:7], 16, v[6:7]
	v_lshl_add_u64 v[4:5], v[4:5], 0, v[162:163]
	v_lshl_or_b32 v6, v2, 8, v6
	v_lshl_add_u64 v[4:5], s[2:3], 0, v[4:5]
	v_lshl_add_u64 v[2:3], s[4:5], 0, v[6:7]
	s_mov_b32 s8, -4
.LBB0_706:
	global_load_dwordx4 v[6:9], v[2:3], off offset:-32 nt
	v_add_co_u32_e32 v10, vcc, 0xfffff000, v4
	s_add_i32 s8, s8, 16
	s_nop 0
	v_addc_co_u32_e32 v11, vcc, -1, v5, vcc
	s_cmp_gt_u32 s8, 59
	s_waitcnt vmcnt(0)
	v_cvt_pk_bf16_f32 v6, v6, s0
	v_cvt_pk_bf16_f32 v7, v7, s0
	v_cvt_pk_bf16_f32 v8, v8, s0
	v_cvt_pk_bf16_f32 v9, v9, s0
	global_store_short v[10:11], v6, off offset:-3584
	global_store_short v[10:11], v7, off offset:-3072
	global_store_short v[10:11], v8, off offset:-2560
	global_store_short v[10:11], v9, off offset:-2048
	global_load_dwordx4 v[6:9], v[2:3], off offset:-16 nt
	s_waitcnt vmcnt(0)
	v_cvt_pk_bf16_f32 v6, v6, s0
	v_cvt_pk_bf16_f32 v7, v7, s0
	v_cvt_pk_bf16_f32 v8, v8, s0
	v_cvt_pk_bf16_f32 v9, v9, s0
	global_store_short v[10:11], v6, off offset:-1536
	global_store_short v[10:11], v7, off offset:-1024
	global_store_short v[10:11], v8, off offset:-512
	global_store_short v[4:5], v9, off offset:-4096
	global_load_dwordx4 v[6:9], v[2:3], off nt
	s_waitcnt vmcnt(0)
	v_cvt_pk_bf16_f32 v6, v6, s0
	v_cvt_pk_bf16_f32 v7, v7, s0
	v_cvt_pk_bf16_f32 v8, v8, s0
	v_cvt_pk_bf16_f32 v9, v9, s0
	global_store_short v[4:5], v6, off offset:-3584
	global_store_short v[4:5], v7, off offset:-3072
	global_store_short v[4:5], v8, off offset:-2560
	global_store_short v[4:5], v9, off offset:-2048
	global_load_dwordx4 v[6:9], v[2:3], off offset:16 nt
	v_lshl_add_u64 v[2:3], v[2:3], 0, 64
	s_waitcnt vmcnt(0)
	v_cvt_pk_bf16_f32 v6, v6, s0
	v_cvt_pk_bf16_f32 v7, v7, s0
	v_cvt_pk_bf16_f32 v8, v8, s0
	v_cvt_pk_bf16_f32 v9, v9, s0
	global_store_short v[4:5], v6, off offset:-1536
	global_store_short v[4:5], v7, off offset:-1024
	global_store_short v[4:5], v8, off offset:-512
	global_store_short v[4:5], v9, off
	v_lshl_add_u64 v[4:5], v[4:5], 0, s[34:35]
	s_cbranch_scc0 .LBB0_706

.LBB0_719:
	v_lshl_add_u64 v[64:65], v[62:63], 0, s[10:11]
	s_waitcnt vmcnt(12)
	v_add_co_u32_e32 v74, vcc, s29, v64
	s_mov_b32 s7, 0xc000
	s_nop 0
	v_addc_co_u32_e32 v75, vcc, 0, v65, vcc
	s_waitcnt vmcnt(9)
	v_add_co_u32_e32 v78, vcc, s7, v64
	s_mov_b32 s7, 0x12000
	s_nop 0
	v_addc_co_u32_e32 v79, vcc, 0, v65, vcc
	v_add_co_u32_e32 v82, vcc, s7, v64
	s_mov_b32 s7, 0x18000
	s_nop 0
	v_addc_co_u32_e32 v83, vcc, 0, v65, vcc
	v_add_co_u32_e32 v86, vcc, s7, v64
	ds_read_b128 v[26:29], v68
	ds_read_b128 v[22:25], v68 offset:16
	ds_read_b128 v[30:33], v68 offset:4096
	ds_read_b128 v[34:37], v68 offset:4112
	ds_read_b128 v[50:53], v68 offset:8192
	ds_read_b128 v[38:41], v68 offset:8208
	ds_read_b128 v[54:57], v68 offset:12288
	ds_read_b128 v[42:45], v68 offset:12304
	ds_read_b128 v[58:61], v68 offset:16384
	ds_read_b128 v[46:49], v68 offset:16400
	global_load_dwordx4 v[70:73], v[64:65], off nt
	v_addc_co_u32_e32 v87, vcc, 0, v65, vcc
	s_mov_b32 s7, 0x1e000
	v_add_co_u32_e32 v90, vcc, s7, v64
	s_mov_b32 s7, 0x24000
	s_nop 0
	v_addc_co_u32_e32 v91, vcc, 0, v65, vcc
	v_add_co_u32_e32 v94, vcc, s7, v64
	s_mov_b32 s7, 0x2a000
	s_nop 0
	v_addc_co_u32_e32 v95, vcc, 0, v65, vcc
	v_add_co_u32_e32 v64, vcc, s7, v64
	global_load_dwordx4 v[74:77], v[74:75], off nt
	s_nop 0
	global_load_dwordx4 v[78:81], v[78:79], off nt
	s_nop 0
	global_load_dwordx4 v[82:85], v[82:83], off nt
	s_nop 0
	global_load_dwordx4 v[86:89], v[86:87], off nt
	s_nop 0
	global_load_dwordx4 v[90:93], v[90:91], off nt
	s_nop 0
	global_load_dwordx4 v[94:97], v[94:95], off nt
	v_addc_co_u32_e32 v65, vcc, 0, v65, vcc
	global_load_dwordx4 v[98:101], v[64:65], off nt
	s_waitcnt lgkmcnt(9)
	v_mov_b32_e32 v64, v29
	s_waitcnt lgkmcnt(7)
	v_mov_b32_e32 v102, v33
	s_waitcnt lgkmcnt(5)
	v_mov_b32_e32 v104, v53
	s_waitcnt lgkmcnt(3)
	v_mov_b32_e32 v106, v57
	s_waitcnt lgkmcnt(1)
	v_mov_b32_e32 v108, v61
	s_add_u32 s10, s10, 0x30000
	s_addc_u32 s11, s11, 0
	v_mov_b32_e32 v110, v25
	v_mov_b32_e32 v112, v37
	v_mov_b32_e32 v114, v41
	v_mov_b32_e32 v116, v45
	s_waitcnt lgkmcnt(0)
	v_mov_b32_e32 v118, v49
	v_add_u32_e32 v68, 32, v68
	s_cmp_eq_u32 s10, 0xc0000
	s_waitcnt vmcnt(7)
	v_pk_fma_f32 v[8:9], v[72:73], v[26:27], v[8:9] op_sel_hi:[1,0,1]
	v_pk_fma_f32 v[6:7], v[70:71], v[26:27], v[6:7] op_sel_hi:[1,0,1]
	v_pk_fma_f32 v[12:13], v[72:73], v[30:31], v[12:13] op_sel_hi:[1,0,1]
	v_pk_fma_f32 v[10:11], v[70:71], v[30:31], v[10:11] op_sel_hi:[1,0,1]
	v_pk_fma_f32 v[16:17], v[72:73], v[50:51], v[16:17] op_sel_hi:[1,0,1]
	v_pk_fma_f32 v[14:15], v[70:71], v[50:51], v[14:15] op_sel_hi:[1,0,1]
	v_pk_fma_f32 v[20:21], v[72:73], v[54:55], v[20:21] op_sel_hi:[1,0,1]
	v_pk_fma_f32 v[18:19], v[70:71], v[54:55], v[18:19] op_sel_hi:[1,0,1]
	v_pk_fma_f32 v[4:5], v[72:73], v[58:59], v[4:5] op_sel_hi:[1,0,1]
	v_pk_fma_f32 v[2:3], v[70:71], v[58:59], v[2:3] op_sel_hi:[1,0,1]
	s_waitcnt vmcnt(6)
	v_pk_fma_f32 v[6:7], v[74:75], v[26:27], v[6:7] op_sel:[0,1,0]
	v_pk_fma_f32 v[8:9], v[76:77], v[26:27], v[8:9] op_sel:[0,1,0]
	v_pk_fma_f32 v[10:11], v[74:75], v[30:31], v[10:11] op_sel:[0,1,0]
	v_pk_fma_f32 v[12:13], v[76:77], v[30:31], v[12:13] op_sel:[0,1,0]
	v_pk_fma_f32 v[14:15], v[74:75], v[50:51], v[14:15] op_sel:[0,1,0]
	v_pk_fma_f32 v[16:17], v[76:77], v[50:51], v[16:17] op_sel:[0,1,0]
	v_pk_fma_f32 v[18:19], v[74:75], v[54:55], v[18:19] op_sel:[0,1,0]
	v_pk_fma_f32 v[20:21], v[76:77], v[54:55], v[20:21] op_sel:[0,1,0]
	v_pk_fma_f32 v[2:3], v[74:75], v[58:59], v[2:3] op_sel:[0,1,0]
	v_pk_fma_f32 v[4:5], v[76:77], v[58:59], v[4:5] op_sel:[0,1,0]
	s_waitcnt vmcnt(5)
	v_pk_fma_f32 v[8:9], v[80:81], v[28:29], v[8:9] op_sel_hi:[1,0,1]
	v_pk_fma_f32 v[6:7], v[78:79], v[28:29], v[6:7] op_sel_hi:[1,0,1]
	v_pk_fma_f32 v[12:13], v[80:81], v[32:33], v[12:13] op_sel_hi:[1,0,1]
	v_pk_fma_f32 v[10:11], v[78:79], v[32:33], v[10:11] op_sel_hi:[1,0,1]
	v_pk_fma_f32 v[16:17], v[80:81], v[52:53], v[16:17] op_sel_hi:[1,0,1]
	v_pk_fma_f32 v[14:15], v[78:79], v[52:53], v[14:15] op_sel_hi:[1,0,1]
	v_pk_fma_f32 v[20:21], v[80:81], v[56:57], v[20:21] op_sel_hi:[1,0,1]
	v_pk_fma_f32 v[18:19], v[78:79], v[56:57], v[18:19] op_sel_hi:[1,0,1]
	v_pk_fma_f32 v[4:5], v[80:81], v[60:61], v[4:5] op_sel_hi:[1,0,1]
	v_pk_fma_f32 v[2:3], v[78:79], v[60:61], v[2:3] op_sel_hi:[1,0,1]
	s_waitcnt vmcnt(4)
	v_pk_fma_f32 v[8:9], v[84:85], v[64:65], v[8:9] op_sel_hi:[1,0,1]
	v_pk_fma_f32 v[6:7], v[82:83], v[64:65], v[6:7] op_sel_hi:[1,0,1]
	v_pk_fma_f32 v[12:13], v[84:85], v[102:103], v[12:13] op_sel_hi:[1,0,1]
	v_pk_fma_f32 v[10:11], v[82:83], v[102:103], v[10:11] op_sel_hi:[1,0,1]
	v_pk_fma_f32 v[16:17], v[84:85], v[104:105], v[16:17] op_sel_hi:[1,0,1]
	v_pk_fma_f32 v[14:15], v[82:83], v[104:105], v[14:15] op_sel_hi:[1,0,1]
	v_pk_fma_f32 v[20:21], v[84:85], v[106:107], v[20:21] op_sel_hi:[1,0,1]
	v_pk_fma_f32 v[18:19], v[82:83], v[106:107], v[18:19] op_sel_hi:[1,0,1]
	v_pk_fma_f32 v[4:5], v[84:85], v[108:109], v[4:5] op_sel_hi:[1,0,1]
	v_pk_fma_f32 v[2:3], v[82:83], v[108:109], v[2:3] op_sel_hi:[1,0,1]
	s_waitcnt vmcnt(3)
	v_pk_fma_f32 v[8:9], v[88:89], v[22:23], v[8:9] op_sel_hi:[1,0,1]
	v_pk_fma_f32 v[6:7], v[86:87], v[22:23], v[6:7] op_sel_hi:[1,0,1]
	v_pk_fma_f32 v[12:13], v[88:89], v[34:35], v[12:13] op_sel_hi:[1,0,1]
	v_pk_fma_f32 v[10:11], v[86:87], v[34:35], v[10:11] op_sel_hi:[1,0,1]
	v_pk_fma_f32 v[16:17], v[88:89], v[38:39], v[16:17] op_sel_hi:[1,0,1]
	v_pk_fma_f32 v[14:15], v[86:87], v[38:39], v[14:15] op_sel_hi:[1,0,1]
	v_pk_fma_f32 v[20:21], v[88:89], v[42:43], v[20:21] op_sel_hi:[1,0,1]
	v_pk_fma_f32 v[18:19], v[86:87], v[42:43], v[18:19] op_sel_hi:[1,0,1]
	v_pk_fma_f32 v[4:5], v[88:89], v[46:47], v[4:5] op_sel_hi:[1,0,1]
	v_pk_fma_f32 v[2:3], v[86:87], v[46:47], v[2:3] op_sel_hi:[1,0,1]
	s_waitcnt vmcnt(2)
	v_pk_fma_f32 v[8:9], v[92:93], v[22:23], v[8:9] op_sel:[0,1,0]
	v_pk_fma_f32 v[6:7], v[90:91], v[22:23], v[6:7] op_sel:[0,1,0]
	v_pk_fma_f32 v[12:13], v[92:93], v[34:35], v[12:13] op_sel:[0,1,0]
	v_pk_fma_f32 v[10:11], v[90:91], v[34:35], v[10:11] op_sel:[0,1,0]
	v_pk_fma_f32 v[16:17], v[92:93], v[38:39], v[16:17] op_sel:[0,1,0]
	v_pk_fma_f32 v[14:15], v[90:91], v[38:39], v[14:15] op_sel:[0,1,0]
	v_pk_fma_f32 v[20:21], v[92:93], v[42:43], v[20:21] op_sel:[0,1,0]
	v_pk_fma_f32 v[18:19], v[90:91], v[42:43], v[18:19] op_sel:[0,1,0]
	v_pk_fma_f32 v[4:5], v[92:93], v[46:47], v[4:5] op_sel:[0,1,0]
	v_pk_fma_f32 v[2:3], v[90:91], v[46:47], v[2:3] op_sel:[0,1,0]
	s_waitcnt vmcnt(1)
	v_pk_fma_f32 v[8:9], v[96:97], v[24:25], v[8:9] op_sel_hi:[1,0,1]
	v_pk_fma_f32 v[6:7], v[94:95], v[24:25], v[6:7] op_sel_hi:[1,0,1]
	v_pk_fma_f32 v[12:13], v[96:97], v[36:37], v[12:13] op_sel_hi:[1,0,1]
	v_pk_fma_f32 v[10:11], v[94:95], v[36:37], v[10:11] op_sel_hi:[1,0,1]
	v_pk_fma_f32 v[16:17], v[96:97], v[40:41], v[16:17] op_sel_hi:[1,0,1]
	v_pk_fma_f32 v[14:15], v[94:95], v[40:41], v[14:15] op_sel_hi:[1,0,1]
	v_pk_fma_f32 v[20:21], v[96:97], v[44:45], v[20:21] op_sel_hi:[1,0,1]
	v_pk_fma_f32 v[18:19], v[94:95], v[44:45], v[18:19] op_sel_hi:[1,0,1]
	v_pk_fma_f32 v[4:5], v[96:97], v[48:49], v[4:5] op_sel_hi:[1,0,1]
	v_pk_fma_f32 v[2:3], v[94:95], v[48:49], v[2:3] op_sel_hi:[1,0,1]
	s_waitcnt vmcnt(0)
	v_pk_fma_f32 v[8:9], v[100:101], v[110:111], v[8:9] op_sel_hi:[1,0,1]
	v_pk_fma_f32 v[6:7], v[98:99], v[110:111], v[6:7] op_sel_hi:[1,0,1]
	v_pk_fma_f32 v[12:13], v[100:101], v[112:113], v[12:13] op_sel_hi:[1,0,1]
	v_pk_fma_f32 v[10:11], v[98:99], v[112:113], v[10:11] op_sel_hi:[1,0,1]
	v_pk_fma_f32 v[16:17], v[100:101], v[114:115], v[16:17] op_sel_hi:[1,0,1]
	v_pk_fma_f32 v[14:15], v[98:99], v[114:115], v[14:15] op_sel_hi:[1,0,1]
	v_pk_fma_f32 v[20:21], v[100:101], v[116:117], v[20:21] op_sel_hi:[1,0,1]
	v_pk_fma_f32 v[18:19], v[98:99], v[116:117], v[18:19] op_sel_hi:[1,0,1]
	v_pk_fma_f32 v[4:5], v[100:101], v[118:119], v[4:5] op_sel_hi:[1,0,1]
	v_pk_fma_f32 v[2:3], v[98:99], v[118:119], v[2:3] op_sel_hi:[1,0,1]
	s_cbranch_scc0 .LBB0_719
	s_movk_i32 s7, 0x500
	v_mul_lo_u32 v22, v67, s7
	s_movk_i32 s7, 0x140
	v_add3_u32 v22, 0, v162, v22
	v_cmp_gt_i32_e32 vcc, s7, v66
	ds_write_b128 v22, v[6:9] offset:20480
	ds_write_b128 v22, v[10:13] offset:20736
	ds_write_b128 v22, v[14:17] offset:20992
	ds_write_b128 v22, v[18:21] offset:21248
	ds_write_b128 v22, v[2:5] offset:21504
	s_waitcnt lgkmcnt(0)
	s_barrier
	s_and_saveexec_b64 s[10:11], vcc
	s_cbranch_execz .LBB0_723
	s_mul_i32 s7, s6, 0x1800
	s_add_i32 s16, s7, s8
	s_mul_i32 s15, s6, 5
	s_lshl_b64 s[6:7], s[8:9], 2
	v_and_b32_e32 v4, 63, v66
	s_add_u32 s6, s24, s6
	v_or_b32_e32 v2, s16, v4
	s_addc_u32 s7, s25, s7
	v_ashrrev_i32_e32 v3, 31, v2
	v_lshlrev_b32_e32 v162, 2, v4
	v_lshl_add_u64 v[2:3], v[2:3], 2, s[64:65]
	v_add_u32_e32 v6, 0, v162
	v_lshl_add_u64 v[4:5], s[6:7], 0, v[162:163]
	s_mov_b64 s[6:7], 0
